# residual GEMM epilogue: row sum-of-squares hops via v_permlane16/32_swap instead of ds_bpermute (on the full bundle)
# baseline (speedup 1.0000x reference)
.Lea_l2:
	s_waitcnt vmcnt(0)
	v_lshlrev_b32_e32 v166, 16, v150
	v_and_b32_e32 v167, 0xffff0000, v150
	v_lshlrev_b32_e32 v150, 16, v151
	v_and_b32_e32 v151, 0xffff0000, v151
	v_pk_fma_f32 v[236:237], v[134:135], v[132:133], v[150:151]
	v_pk_fma_f32 v[238:239], v[136:137], v[130:131], v[166:167]
	v_lshlrev_b32_e32 v130, 16, v152
	v_and_b32_e32 v131, 0xffff0000, v152
	v_lshlrev_b32_e32 v132, 16, v153
	v_and_b32_e32 v133, 0xffff0000, v153
	v_pk_fma_f32 v[232:233], v[134:135], v[128:129], v[132:133]
	v_pk_fma_f32 v[234:235], v[136:137], v[126:127], v[130:131]
	v_lshlrev_b32_e32 v126, 16, v158
	v_and_b32_e32 v127, 0xffff0000, v158
	v_lshlrev_b32_e32 v128, 16, v159
	v_and_b32_e32 v129, 0xffff0000, v159
	v_pk_fma_f32 v[228:229], v[134:135], v[124:125], v[128:129]
	v_pk_fma_f32 v[230:231], v[136:137], v[122:123], v[126:127]
	v_lshlrev_b32_e32 v124, 16, v163
	v_and_b32_e32 v125, 0xffff0000, v163
	v_add_u32_e32 v126, 0x90, v214
	v_lshlrev_b32_e32 v122, 16, v162
	v_and_b32_e32 v123, 0xffff0000, v162
	v_pk_fma_f32 v[224:225], v[134:135], v[120:121], v[124:125]
	v_lshlrev_b64 v[150:151], 11, v[144:145]
	v_ashrrev_i32_e32 v127, 31, v126
	v_add_u32_e32 v120, 0xa0, v214
	v_pk_fma_f32 v[226:227], v[136:137], v[118:119], v[122:123]
	v_lshl_add_u64 v[118:119], v[182:183], 0, v[150:151]
	v_lshlrev_b64 v[168:169], 11, v[126:127]
	v_ashrrev_i32_e32 v121, 31, v120
	global_load_dwordx2 v[172:173], v[118:119], off
	global_load_dwordx2 v[166:167], v[118:119], off offset:32
	global_load_dwordx2 v[162:163], v[118:119], off offset:256
	global_load_dwordx2 v[158:159], v[118:119], off offset:288
	v_lshl_add_u64 v[118:119], v[182:183], 0, v[168:169]
	v_lshlrev_b64 v[124:125], 11, v[120:121]
	global_load_dwordx2 v[194:195], v[118:119], off
	global_load_dwordx2 v[188:189], v[118:119], off offset:32
	global_load_dwordx2 v[184:185], v[118:119], off offset:256
	global_load_dwordx2 v[174:175], v[118:119], off offset:288
	v_lshl_add_u64 v[118:119], v[182:183], 0, v[124:125]
	global_load_dwordx2 v[152:153], v[118:119], off
	global_load_dwordx2 v[132:133], v[118:119], off offset:32
	global_load_dwordx2 v[130:131], v[118:119], off offset:256
	global_load_dwordx2 v[128:129], v[118:119], off offset:288
	v_add_u32_e32 v118, 0xb0, v214
	v_ashrrev_i32_e32 v119, 31, v118
	v_lshlrev_b64 v[122:123], 11, v[118:119]
	v_lshl_add_u64 v[182:183], v[182:183], 0, v[122:123]
	global_load_dwordx2 v[196:197], v[182:183], off
	global_load_dwordx2 v[190:191], v[182:183], off offset:32
	global_load_dwordx2 v[186:187], v[182:183], off offset:256
	s_nop 0
	global_load_dwordx2 v[182:183], v[182:183], off offset:288
	v_cvt_pk_bf16_f32 v222, v238, v239
	v_cvt_pk_bf16_f32 v223, v236, v237
	global_store_dwordx2 v[220:221], v[222:223], off
	v_mul_f32_e32 v222, v239, v239
	v_mul_f32_e32 v223, v237, v237
	v_fmac_f32_e32 v222, v238, v238
	v_fmac_f32_e32 v223, v236, v236
	v_add_f32_e32 v236, v222, v223
	v_cvt_pk_bf16_f32 v222, v234, v235
	v_cvt_pk_bf16_f32 v223, v232, v233
	global_store_dwordx2 v[220:221], v[222:223], off offset:32
	v_mul_f32_e32 v222, v235, v235
	v_mul_f32_e32 v223, v233, v233
	v_fmac_f32_e32 v222, v234, v234
	v_fmac_f32_e32 v223, v232, v232
	v_add_f32_e32 v222, v222, v223
	v_add_f32_e32 v232, v236, v222
	v_cvt_pk_bf16_f32 v222, v230, v231
	v_cvt_pk_bf16_f32 v223, v228, v229
	global_store_dwordx2 v[220:221], v[222:223], off offset:256
	v_mul_f32_e32 v222, v231, v231
	v_mul_f32_e32 v223, v229, v229
	v_fmac_f32_e32 v222, v230, v230
	v_fmac_f32_e32 v223, v228, v228
	v_add_f32_e32 v222, v222, v223
	v_add_f32_e32 v228, v232, v222
	v_cvt_pk_bf16_f32 v222, v226, v227
	v_cvt_pk_bf16_f32 v223, v224, v225
	global_store_dwordx2 v[220:221], v[222:223], off offset:288
	v_mul_f32_e32 v220, v227, v227
	v_mul_f32_e32 v221, v225, v225
	v_fmac_f32_e32 v220, v226, v226
	v_fmac_f32_e32 v221, v224, v224
	v_add_f32_e32 v220, v220, v221
	v_add_f32_e32 v220, v228, v220
	v_mov_b32_e32 v221, v220
	s_nop 1
	v_permlane16_swap_b32 v220, v221
	s_nop 1
	s_waitcnt lgkmcnt(0)
	v_add_f32_e32 v220, v220, v221
	v_mov_b32_e32 v221, v220
	s_nop 1
	v_permlane32_swap_b32 v220, v221
	s_nop 1
	s_and_saveexec_b64 s[24:25], s[0:1]
	s_cbranch_execz .LBB0_642
	v_lshlrev_b64 v[214:215], 6, v[214:215]
	v_lshl_add_u64 v[214:215], s[22:23], 0, v[214:215]
	s_waitcnt lgkmcnt(0)
	v_add_f32_e32 v220, v220, v221
	global_store_dword v[214:215], v220, off
.LBB0_642:
	s_or_b64 exec, exec, s[24:25]
	v_lshlrev_b32_e32 v214, 16, v218
	v_and_b32_e32 v215, 0xffff0000, v218
	v_pk_fma_f32 v[114:115], v[136:137], v[114:115], v[214:215]
	v_lshlrev_b32_e32 v214, 16, v216
	v_and_b32_e32 v215, 0xffff0000, v216
	v_pk_fma_f32 v[110:111], v[136:137], v[110:111], v[214:215]
	v_lshlrev_b32_e32 v214, 16, v212
	v_and_b32_e32 v215, 0xffff0000, v212
	v_lshlrev_b32_e32 v212, 16, v213
	v_and_b32_e32 v213, 0xffff0000, v213
	v_lshlrev_b32_e32 v218, 16, v219
	v_and_b32_e32 v219, 0xffff0000, v219
	v_pk_fma_f32 v[108:109], v[134:135], v[108:109], v[212:213]
	v_lshlrev_b32_e32 v212, 16, v210
	v_and_b32_e32 v213, 0xffff0000, v210
	v_lshlrev_b32_e32 v210, 16, v211
	v_and_b32_e32 v211, 0xffff0000, v211
	v_pk_fma_f32 v[116:117], v[134:135], v[116:117], v[218:219]
	v_pk_fma_f32 v[104:105], v[134:135], v[104:105], v[210:211]
	v_pk_fma_f32 v[210:211], v[136:137], v[102:103], v[212:213]
	v_lshl_add_u64 v[102:103], s[84:85], 0, v[208:209]
	v_lshl_add_u64 v[208:209], v[142:143], 1, v[102:103]
	v_cvt_pk_bf16_f32 v102, v114, v115
	v_cvt_pk_bf16_f32 v103, v116, v117
	global_store_dwordx2 v[208:209], v[102:103], off
	v_mul_f32_e32 v102, v115, v115
	v_mul_f32_e32 v103, v117, v117
	v_lshlrev_b32_e32 v216, 16, v217
	v_and_b32_e32 v217, 0xffff0000, v217
	v_fmac_f32_e32 v102, v114, v114
	v_fmac_f32_e32 v103, v116, v116
	v_pk_fma_f32 v[112:113], v[134:135], v[112:113], v[216:217]
	v_add_f32_e32 v103, v102, v103
	v_cvt_pk_bf16_f32 v102, v110, v111
	v_mul_f32_e32 v111, v111, v111
	v_fmac_f32_e32 v111, v110, v110
	v_mul_f32_e32 v110, v113, v113
	v_fmac_f32_e32 v110, v112, v112
	v_pk_fma_f32 v[106:107], v[136:137], v[106:107], v[214:215]
	v_add_f32_e32 v110, v111, v110
	v_add_f32_e32 v103, v103, v110
	v_mul_f32_e32 v110, v107, v107
	v_mul_f32_e32 v111, v109, v109
	v_fmac_f32_e32 v110, v106, v106
	v_fmac_f32_e32 v111, v108, v108
	v_add_f32_e32 v110, v110, v111
	v_add_f32_e32 v103, v103, v110
	v_mul_f32_e32 v110, v211, v211
	v_mul_f32_e32 v111, v105, v105
	v_fmac_f32_e32 v110, v210, v210
	v_fmac_f32_e32 v111, v104, v104
	v_add_f32_e32 v110, v110, v111
	v_add_f32_e32 v110, v103, v110
	v_mov_b32_e32 v111, v110
	s_nop 1
	v_permlane16_swap_b32 v110, v111
	s_nop 1
	v_cvt_pk_bf16_f32 v103, v112, v113
	global_store_dwordx2 v[208:209], v[102:103], off offset:32
	v_cvt_pk_bf16_f32 v106, v106, v107
	v_cvt_pk_bf16_f32 v107, v108, v109
	s_waitcnt lgkmcnt(0)
	v_add_f32_e32 v102, v110, v111
	v_mov_b32_e32 v103, v102
	s_nop 1
	v_permlane32_swap_b32 v102, v103
	s_nop 1
	global_store_dwordx2 v[208:209], v[106:107], off offset:256
	v_cvt_pk_bf16_f32 v106, v210, v211
	v_cvt_pk_bf16_f32 v107, v104, v105
	global_store_dwordx2 v[208:209], v[106:107], off offset:288
	s_and_saveexec_b64 s[24:25], s[0:1]
	s_cbranch_execz .LBB0_644
	v_lshlrev_b64 v[104:105], 6, v[200:201]
	v_lshl_add_u64 v[104:105], s[22:23], 0, v[104:105]
	s_waitcnt lgkmcnt(0)
	v_add_f32_e32 v102, v102, v103
	global_store_dword v[104:105], v102, off
.LBB0_644:
	s_or_b64 exec, exec, s[24:25]
	v_lshlrev_b32_e32 v102, 16, v206
	s_waitcnt lgkmcnt(0)
	v_and_b32_e32 v103, 0xffff0000, v206
	v_lshlrev_b32_e32 v104, 16, v207
	v_and_b32_e32 v105, 0xffff0000, v207
	v_mov_b32_e32 v135, v134
	v_pk_fma_f32 v[98:99], v[136:137], v[98:99], v[102:103]
	v_lshlrev_b32_e32 v102, 16, v204
	v_and_b32_e32 v103, 0xffff0000, v204
	v_pk_fma_f32 v[100:101], v[134:135], v[100:101], v[104:105]
	v_lshlrev_b32_e32 v104, 16, v205
	v_and_b32_e32 v105, 0xffff0000, v205
	v_pk_fma_f32 v[94:95], v[136:137], v[94:95], v[102:103]
	v_lshlrev_b32_e32 v102, 16, v202
	v_and_b32_e32 v103, 0xffff0000, v202
	v_pk_fma_f32 v[96:97], v[134:135], v[96:97], v[104:105]
	v_lshlrev_b32_e32 v104, 16, v203
	v_and_b32_e32 v105, 0xffff0000, v203
	v_pk_fma_f32 v[90:91], v[136:137], v[90:91], v[102:103]
	v_lshlrev_b32_e32 v102, 16, v198
	v_and_b32_e32 v103, 0xffff0000, v198
	v_pk_fma_f32 v[92:93], v[134:135], v[92:93], v[104:105]
	v_lshlrev_b32_e32 v104, 16, v199
	v_and_b32_e32 v105, 0xffff0000, v199
	v_pk_fma_f32 v[102:103], v[136:137], v[86:87], v[102:103]
	v_lshl_add_u64 v[86:87], s[84:85], 0, v[192:193]
	v_pk_fma_f32 v[88:89], v[134:135], v[88:89], v[104:105]
	v_lshl_add_u64 v[104:105], v[142:143], 1, v[86:87]
	v_cvt_pk_bf16_f32 v86, v98, v99
	v_cvt_pk_bf16_f32 v87, v100, v101
	global_store_dwordx2 v[104:105], v[86:87], off
	v_mul_f32_e32 v86, v99, v99
	v_mul_f32_e32 v87, v101, v101
	v_fmac_f32_e32 v86, v98, v98
	v_fmac_f32_e32 v87, v100, v100
	v_add_f32_e32 v87, v86, v87
	v_cvt_pk_bf16_f32 v86, v94, v95
	v_mul_f32_e32 v95, v95, v95
	v_fmac_f32_e32 v95, v94, v94
	v_mul_f32_e32 v94, v97, v97
	v_fmac_f32_e32 v94, v96, v96
	v_add_f32_e32 v94, v95, v94
	v_add_f32_e32 v87, v87, v94
	v_mul_f32_e32 v94, v91, v91
	v_mul_f32_e32 v95, v93, v93
	v_fmac_f32_e32 v94, v90, v90
	v_fmac_f32_e32 v95, v92, v92
	v_add_f32_e32 v94, v94, v95
	v_add_f32_e32 v87, v87, v94
	v_mul_f32_e32 v94, v103, v103
	v_mul_f32_e32 v95, v89, v89
	v_fmac_f32_e32 v94, v102, v102
	v_fmac_f32_e32 v95, v88, v88
	v_add_f32_e32 v94, v94, v95
	v_add_f32_e32 v94, v87, v94
	v_mov_b32_e32 v95, v94
	s_nop 1
	v_permlane16_swap_b32 v94, v95
	s_nop 1
	v_cvt_pk_bf16_f32 v87, v96, v97
	global_store_dwordx2 v[104:105], v[86:87], off offset:32
	v_cvt_pk_bf16_f32 v90, v90, v91
	v_cvt_pk_bf16_f32 v91, v92, v93
	s_waitcnt lgkmcnt(0)
	v_add_f32_e32 v86, v94, v95
	v_mov_b32_e32 v87, v86
	s_nop 1
	v_permlane32_swap_b32 v86, v87
	s_nop 1
	global_store_dwordx2 v[104:105], v[90:91], off offset:256
	v_cvt_pk_bf16_f32 v90, v102, v103
	v_cvt_pk_bf16_f32 v91, v88, v89
	global_store_dwordx2 v[104:105], v[90:91], off offset:288
	s_and_saveexec_b64 s[24:25], s[0:1]
	s_cbranch_execz .LBB0_646
	v_lshlrev_b64 v[88:89], 6, v[156:157]
	v_lshl_add_u64 v[88:89], s[22:23], 0, v[88:89]
	s_waitcnt lgkmcnt(0)
	v_add_f32_e32 v86, v86, v87
	global_store_dword v[88:89], v86, off
.LBB0_646:
	s_or_b64 exec, exec, s[24:25]
	v_lshlrev_b32_e32 v86, 16, v170
	s_waitcnt lgkmcnt(0)
	v_and_b32_e32 v87, 0xffff0000, v170
	v_lshlrev_b32_e32 v88, 16, v171
	v_and_b32_e32 v89, 0xffff0000, v171
	v_pk_fma_f32 v[82:83], v[136:137], v[82:83], v[86:87]
	v_lshlrev_b32_e32 v86, 16, v164
	v_and_b32_e32 v87, 0xffff0000, v164
	v_pk_fma_f32 v[84:85], v[134:135], v[84:85], v[88:89]
	v_lshlrev_b32_e32 v88, 16, v165
	v_and_b32_e32 v89, 0xffff0000, v165
	v_pk_fma_f32 v[78:79], v[136:137], v[78:79], v[86:87]
	v_lshlrev_b32_e32 v86, 16, v160
	v_and_b32_e32 v87, 0xffff0000, v160
	v_pk_fma_f32 v[80:81], v[134:135], v[80:81], v[88:89]
	v_lshlrev_b32_e32 v88, 16, v161
	v_and_b32_e32 v89, 0xffff0000, v161
	v_pk_fma_f32 v[74:75], v[136:137], v[74:75], v[86:87]
	v_lshlrev_b32_e32 v86, 16, v154
	v_and_b32_e32 v87, 0xffff0000, v154
	v_pk_fma_f32 v[76:77], v[134:135], v[76:77], v[88:89]
	v_lshlrev_b32_e32 v88, 16, v155
	v_and_b32_e32 v89, 0xffff0000, v155
	v_pk_fma_f32 v[86:87], v[136:137], v[70:71], v[86:87]
	v_lshl_add_u64 v[70:71], s[84:85], 0, v[148:149]
	v_pk_fma_f32 v[72:73], v[134:135], v[72:73], v[88:89]
	v_lshl_add_u64 v[88:89], v[142:143], 1, v[70:71]
	v_cvt_pk_bf16_f32 v70, v82, v83
	v_cvt_pk_bf16_f32 v71, v84, v85
	global_store_dwordx2 v[88:89], v[70:71], off
	v_mul_f32_e32 v70, v83, v83
	v_mul_f32_e32 v71, v85, v85
	v_fmac_f32_e32 v70, v82, v82
	v_fmac_f32_e32 v71, v84, v84
	v_add_f32_e32 v71, v70, v71
	v_cvt_pk_bf16_f32 v70, v78, v79
	v_mul_f32_e32 v79, v79, v79
	v_fmac_f32_e32 v79, v78, v78
	v_mul_f32_e32 v78, v81, v81
	v_fmac_f32_e32 v78, v80, v80
	v_add_f32_e32 v78, v79, v78
	v_add_f32_e32 v71, v71, v78
	v_mul_f32_e32 v78, v75, v75
	v_mul_f32_e32 v79, v77, v77
	v_fmac_f32_e32 v78, v74, v74
	v_fmac_f32_e32 v79, v76, v76
	v_add_f32_e32 v78, v78, v79
	v_add_f32_e32 v71, v71, v78
	v_mul_f32_e32 v78, v87, v87
	v_mul_f32_e32 v79, v73, v73
	v_fmac_f32_e32 v78, v86, v86
	v_fmac_f32_e32 v79, v72, v72
	v_add_f32_e32 v78, v78, v79
	v_add_f32_e32 v78, v71, v78
	v_mov_b32_e32 v79, v78
	s_nop 1
	v_permlane16_swap_b32 v78, v79
	s_nop 1
	v_cvt_pk_bf16_f32 v71, v80, v81
	global_store_dwordx2 v[88:89], v[70:71], off offset:32
	v_cvt_pk_bf16_f32 v74, v74, v75
	v_cvt_pk_bf16_f32 v75, v76, v77
	s_waitcnt lgkmcnt(0)
	v_add_f32_e32 v70, v78, v79
	v_mov_b32_e32 v71, v70
	s_nop 1
	v_permlane32_swap_b32 v70, v71
	s_nop 1
	global_store_dwordx2 v[88:89], v[74:75], off offset:256
	v_cvt_pk_bf16_f32 v74, v86, v87
	v_cvt_pk_bf16_f32 v75, v72, v73
	global_store_dwordx2 v[88:89], v[74:75], off offset:288
	s_and_saveexec_b64 s[24:25], s[0:1]
	s_cbranch_execz .LBB0_648
	v_lshlrev_b64 v[72:73], 6, v[146:147]
	v_lshl_add_u64 v[72:73], s[22:23], 0, v[72:73]
	s_waitcnt lgkmcnt(0)
	v_add_f32_e32 v70, v70, v71
	global_store_dword v[72:73], v70, off
.LBB0_648:
	s_or_b64 exec, exec, s[24:25]
	s_waitcnt vmcnt(31)
	v_lshlrev_b32_e32 v70, 16, v172
	s_waitcnt lgkmcnt(0)
	v_and_b32_e32 v71, 0xffff0000, v172
	v_lshlrev_b32_e32 v72, 16, v173
	v_and_b32_e32 v73, 0xffff0000, v173
	v_mov_b32_e32 v135, v134
	v_pk_fma_f32 v[66:67], v[136:137], v[66:67], v[70:71]
	s_waitcnt vmcnt(30)
	v_lshlrev_b32_e32 v70, 16, v166
	v_and_b32_e32 v71, 0xffff0000, v166
	v_pk_fma_f32 v[68:69], v[134:135], v[68:69], v[72:73]
	v_lshlrev_b32_e32 v72, 16, v167
	v_and_b32_e32 v73, 0xffff0000, v167
	v_pk_fma_f32 v[62:63], v[136:137], v[62:63], v[70:71]
	s_waitcnt vmcnt(29)
	v_lshlrev_b32_e32 v70, 16, v162
	v_and_b32_e32 v71, 0xffff0000, v162
	v_pk_fma_f32 v[64:65], v[134:135], v[64:65], v[72:73]
	v_lshlrev_b32_e32 v72, 16, v163
	v_and_b32_e32 v73, 0xffff0000, v163
	v_pk_fma_f32 v[58:59], v[136:137], v[58:59], v[70:71]
	s_waitcnt vmcnt(28)
	v_lshlrev_b32_e32 v70, 16, v158
	v_and_b32_e32 v71, 0xffff0000, v158
	v_pk_fma_f32 v[60:61], v[134:135], v[60:61], v[72:73]
	v_lshlrev_b32_e32 v72, 16, v159
	v_and_b32_e32 v73, 0xffff0000, v159
	v_pk_fma_f32 v[70:71], v[136:137], v[54:55], v[70:71]
	v_lshl_add_u64 v[54:55], s[84:85], 0, v[150:151]
	v_pk_fma_f32 v[56:57], v[134:135], v[56:57], v[72:73]
	v_lshl_add_u64 v[72:73], v[142:143], 1, v[54:55]
	v_cvt_pk_bf16_f32 v54, v66, v67
	v_cvt_pk_bf16_f32 v55, v68, v69
	global_store_dwordx2 v[72:73], v[54:55], off
	v_mul_f32_e32 v54, v67, v67
	v_mul_f32_e32 v55, v69, v69
	v_fmac_f32_e32 v54, v66, v66
	v_fmac_f32_e32 v55, v68, v68
	v_add_f32_e32 v55, v54, v55
	v_cvt_pk_bf16_f32 v54, v62, v63
	v_mul_f32_e32 v63, v63, v63
	v_fmac_f32_e32 v63, v62, v62
	v_mul_f32_e32 v62, v65, v65
	v_fmac_f32_e32 v62, v64, v64
	v_add_f32_e32 v62, v63, v62
	v_add_f32_e32 v55, v55, v62
	v_mul_f32_e32 v62, v59, v59
	v_mul_f32_e32 v63, v61, v61
	v_fmac_f32_e32 v62, v58, v58
	v_fmac_f32_e32 v63, v60, v60
	v_add_f32_e32 v62, v62, v63
	v_add_f32_e32 v55, v55, v62
	v_mul_f32_e32 v62, v71, v71
	v_mul_f32_e32 v63, v57, v57
	v_fmac_f32_e32 v62, v70, v70
	v_fmac_f32_e32 v63, v56, v56
	v_add_f32_e32 v62, v62, v63
	v_add_f32_e32 v62, v55, v62
	v_mov_b32_e32 v63, v62
	s_nop 1
	v_permlane16_swap_b32 v62, v63
	s_nop 1
	v_cvt_pk_bf16_f32 v55, v64, v65
	global_store_dwordx2 v[72:73], v[54:55], off offset:32
	v_cvt_pk_bf16_f32 v58, v58, v59
	v_cvt_pk_bf16_f32 v59, v60, v61
	s_waitcnt lgkmcnt(0)
	v_add_f32_e32 v54, v62, v63
	v_mov_b32_e32 v55, v54
	s_nop 1
	v_permlane32_swap_b32 v54, v55
	s_nop 1
	global_store_dwordx2 v[72:73], v[58:59], off offset:256
	v_cvt_pk_bf16_f32 v58, v70, v71
	v_cvt_pk_bf16_f32 v59, v56, v57
	global_store_dwordx2 v[72:73], v[58:59], off offset:288
	s_and_saveexec_b64 s[24:25], s[0:1]
	s_cbranch_execz .LBB0_650
	v_lshlrev_b64 v[56:57], 6, v[144:145]
	v_lshl_add_u64 v[56:57], s[22:23], 0, v[56:57]
	s_waitcnt lgkmcnt(0)
	v_add_f32_e32 v54, v54, v55
	global_store_dword v[56:57], v54, off
.LBB0_650:
	s_or_b64 exec, exec, s[24:25]
	s_waitcnt vmcnt(31)
	v_lshlrev_b32_e32 v54, 16, v194
	s_waitcnt lgkmcnt(0)
	v_and_b32_e32 v55, 0xffff0000, v194
	v_lshlrev_b32_e32 v56, 16, v195
	v_and_b32_e32 v57, 0xffff0000, v195
	v_pk_fma_f32 v[50:51], v[136:137], v[50:51], v[54:55]
	s_waitcnt vmcnt(30)
	v_lshlrev_b32_e32 v54, 16, v188
	v_and_b32_e32 v55, 0xffff0000, v188
	v_pk_fma_f32 v[52:53], v[134:135], v[52:53], v[56:57]
	v_lshlrev_b32_e32 v56, 16, v189
	v_and_b32_e32 v57, 0xffff0000, v189
	v_pk_fma_f32 v[46:47], v[136:137], v[46:47], v[54:55]
	s_waitcnt vmcnt(29)
	v_lshlrev_b32_e32 v54, 16, v184
	v_and_b32_e32 v55, 0xffff0000, v184
	v_pk_fma_f32 v[48:49], v[134:135], v[48:49], v[56:57]
	v_lshlrev_b32_e32 v56, 16, v185
	v_and_b32_e32 v57, 0xffff0000, v185
	v_pk_fma_f32 v[42:43], v[136:137], v[42:43], v[54:55]
	s_waitcnt vmcnt(28)
	v_lshlrev_b32_e32 v54, 16, v174
	v_and_b32_e32 v55, 0xffff0000, v174
	v_pk_fma_f32 v[44:45], v[134:135], v[44:45], v[56:57]
	v_lshlrev_b32_e32 v56, 16, v175
	v_and_b32_e32 v57, 0xffff0000, v175
	v_pk_fma_f32 v[54:55], v[136:137], v[38:39], v[54:55]
	v_lshl_add_u64 v[38:39], s[84:85], 0, v[168:169]
	v_pk_fma_f32 v[40:41], v[134:135], v[40:41], v[56:57]
	v_lshl_add_u64 v[56:57], v[142:143], 1, v[38:39]
	v_cvt_pk_bf16_f32 v38, v50, v51
	v_cvt_pk_bf16_f32 v39, v52, v53
	global_store_dwordx2 v[56:57], v[38:39], off
	v_mul_f32_e32 v38, v51, v51
	v_mul_f32_e32 v39, v53, v53
	v_fmac_f32_e32 v38, v50, v50
	v_fmac_f32_e32 v39, v52, v52
	v_add_f32_e32 v39, v38, v39
	v_cvt_pk_bf16_f32 v38, v46, v47
	v_mul_f32_e32 v47, v47, v47
	v_fmac_f32_e32 v47, v46, v46
	v_mul_f32_e32 v46, v49, v49
	v_fmac_f32_e32 v46, v48, v48
	v_add_f32_e32 v46, v47, v46
	v_add_f32_e32 v39, v39, v46
	v_mul_f32_e32 v46, v43, v43
	v_mul_f32_e32 v47, v45, v45
	v_fmac_f32_e32 v46, v42, v42
	v_fmac_f32_e32 v47, v44, v44
	v_add_f32_e32 v46, v46, v47
	v_add_f32_e32 v39, v39, v46
	v_mul_f32_e32 v46, v55, v55
	v_mul_f32_e32 v47, v41, v41
	v_fmac_f32_e32 v46, v54, v54
	v_fmac_f32_e32 v47, v40, v40
	v_add_f32_e32 v46, v46, v47
	v_add_f32_e32 v46, v39, v46
	v_mov_b32_e32 v47, v46
	s_nop 1
	v_permlane16_swap_b32 v46, v47
	s_nop 1
	v_cvt_pk_bf16_f32 v39, v48, v49
	global_store_dwordx2 v[56:57], v[38:39], off offset:32
	v_cvt_pk_bf16_f32 v42, v42, v43
	v_cvt_pk_bf16_f32 v43, v44, v45
	s_waitcnt lgkmcnt(0)
	v_add_f32_e32 v38, v46, v47
	v_mov_b32_e32 v39, v38
	s_nop 1
	v_permlane32_swap_b32 v38, v39
	s_nop 1
	global_store_dwordx2 v[56:57], v[42:43], off offset:256
	v_cvt_pk_bf16_f32 v42, v54, v55
	v_cvt_pk_bf16_f32 v43, v40, v41
	global_store_dwordx2 v[56:57], v[42:43], off offset:288
	s_and_saveexec_b64 s[24:25], s[0:1]
	s_cbranch_execz .LBB0_652
	v_lshlrev_b64 v[40:41], 6, v[126:127]
	v_lshl_add_u64 v[40:41], s[22:23], 0, v[40:41]
	s_waitcnt lgkmcnt(0)
	v_add_f32_e32 v38, v38, v39
	global_store_dword v[40:41], v38, off
.LBB0_652:
	s_or_b64 exec, exec, s[24:25]
	s_waitcnt vmcnt(31)
	v_lshlrev_b32_e32 v38, 16, v152
	s_waitcnt lgkmcnt(0)
	v_and_b32_e32 v39, 0xffff0000, v152
	v_lshlrev_b32_e32 v40, 16, v153
	v_and_b32_e32 v41, 0xffff0000, v153
	v_mov_b32_e32 v135, v134
	v_pk_fma_f32 v[34:35], v[136:137], v[34:35], v[38:39]
	s_waitcnt vmcnt(30)
	v_lshlrev_b32_e32 v38, 16, v132
	v_and_b32_e32 v39, 0xffff0000, v132
	v_pk_fma_f32 v[36:37], v[134:135], v[36:37], v[40:41]
	v_lshlrev_b32_e32 v40, 16, v133
	v_and_b32_e32 v41, 0xffff0000, v133
	v_pk_fma_f32 v[30:31], v[136:137], v[30:31], v[38:39]
	s_waitcnt vmcnt(29)
	v_lshlrev_b32_e32 v38, 16, v130
	v_and_b32_e32 v39, 0xffff0000, v130
	v_pk_fma_f32 v[32:33], v[134:135], v[32:33], v[40:41]
	v_lshlrev_b32_e32 v40, 16, v131
	v_and_b32_e32 v41, 0xffff0000, v131
	v_pk_fma_f32 v[26:27], v[136:137], v[26:27], v[38:39]
	s_waitcnt vmcnt(28)
	v_lshlrev_b32_e32 v38, 16, v128
	v_and_b32_e32 v39, 0xffff0000, v128
	v_pk_fma_f32 v[28:29], v[134:135], v[28:29], v[40:41]
	v_lshlrev_b32_e32 v40, 16, v129
	v_and_b32_e32 v41, 0xffff0000, v129
	v_pk_fma_f32 v[38:39], v[136:137], v[22:23], v[38:39]
	v_lshl_add_u64 v[22:23], s[84:85], 0, v[124:125]
	v_pk_fma_f32 v[24:25], v[134:135], v[24:25], v[40:41]
	v_lshl_add_u64 v[40:41], v[142:143], 1, v[22:23]
	v_cvt_pk_bf16_f32 v22, v34, v35
	v_cvt_pk_bf16_f32 v23, v36, v37
	global_store_dwordx2 v[40:41], v[22:23], off
	v_mul_f32_e32 v22, v35, v35
	v_mul_f32_e32 v23, v37, v37
	v_fmac_f32_e32 v22, v34, v34
	v_fmac_f32_e32 v23, v36, v36
	v_add_f32_e32 v23, v22, v23
	v_cvt_pk_bf16_f32 v22, v30, v31
	v_mul_f32_e32 v31, v31, v31
	v_fmac_f32_e32 v31, v30, v30
	v_mul_f32_e32 v30, v33, v33
	v_fmac_f32_e32 v30, v32, v32
	v_add_f32_e32 v30, v31, v30
	v_add_f32_e32 v23, v23, v30
	v_mul_f32_e32 v30, v27, v27
	v_mul_f32_e32 v31, v29, v29
	v_fmac_f32_e32 v30, v26, v26
	v_fmac_f32_e32 v31, v28, v28
	v_add_f32_e32 v30, v30, v31
	v_add_f32_e32 v23, v23, v30
	v_mul_f32_e32 v30, v39, v39
	v_mul_f32_e32 v31, v25, v25
	v_fmac_f32_e32 v30, v38, v38
	v_fmac_f32_e32 v31, v24, v24
	v_add_f32_e32 v30, v30, v31
	v_add_f32_e32 v30, v23, v30
	v_mov_b32_e32 v31, v30
	s_nop 1
	v_permlane16_swap_b32 v30, v31
	s_nop 1
	v_cvt_pk_bf16_f32 v23, v32, v33
	global_store_dwordx2 v[40:41], v[22:23], off offset:32
	v_cvt_pk_bf16_f32 v26, v26, v27
	v_cvt_pk_bf16_f32 v27, v28, v29
	s_waitcnt lgkmcnt(0)
	v_add_f32_e32 v22, v30, v31
	v_mov_b32_e32 v23, v22
	s_nop 1
	v_permlane32_swap_b32 v22, v23
	s_nop 1
	global_store_dwordx2 v[40:41], v[26:27], off offset:256
	v_cvt_pk_bf16_f32 v26, v38, v39
	v_cvt_pk_bf16_f32 v27, v24, v25
	global_store_dwordx2 v[40:41], v[26:27], off offset:288
	s_and_saveexec_b64 s[24:25], s[0:1]
	s_cbranch_execz .LBB0_654
	v_lshlrev_b64 v[24:25], 6, v[120:121]
	v_lshl_add_u64 v[24:25], s[22:23], 0, v[24:25]
	s_waitcnt lgkmcnt(0)
	v_add_f32_e32 v22, v22, v23
	global_store_dword v[24:25], v22, off
.LBB0_654:
	s_or_b64 exec, exec, s[24:25]
	s_waitcnt vmcnt(31)
	v_lshlrev_b32_e32 v22, 16, v196
	s_waitcnt lgkmcnt(0)
	v_and_b32_e32 v23, 0xffff0000, v196
	v_lshlrev_b32_e32 v24, 16, v197
	v_and_b32_e32 v25, 0xffff0000, v197
	v_pk_fma_f32 v[18:19], v[136:137], v[18:19], v[22:23]
	s_waitcnt vmcnt(30)
	v_lshlrev_b32_e32 v22, 16, v190
	v_and_b32_e32 v23, 0xffff0000, v190
	v_pk_fma_f32 v[20:21], v[134:135], v[20:21], v[24:25]
	v_lshlrev_b32_e32 v24, 16, v191
	v_and_b32_e32 v25, 0xffff0000, v191
	v_pk_fma_f32 v[10:11], v[136:137], v[10:11], v[22:23]
	s_waitcnt vmcnt(29)
	v_lshlrev_b32_e32 v22, 16, v186
	v_and_b32_e32 v23, 0xffff0000, v186
	v_pk_fma_f32 v[12:13], v[134:135], v[12:13], v[24:25]
	v_lshlrev_b32_e32 v24, 16, v187
	v_and_b32_e32 v25, 0xffff0000, v187
	v_pk_fma_f32 v[6:7], v[136:137], v[6:7], v[22:23]
	s_waitcnt vmcnt(28)
	v_lshlrev_b32_e32 v22, 16, v182
	v_and_b32_e32 v23, 0xffff0000, v182
	v_pk_fma_f32 v[8:9], v[134:135], v[8:9], v[24:25]
	v_lshlrev_b32_e32 v24, 16, v183
	v_and_b32_e32 v25, 0xffff0000, v183
	v_pk_fma_f32 v[22:23], v[136:137], v[2:3], v[22:23]
	v_lshl_add_u64 v[2:3], s[84:85], 0, v[122:123]
	v_pk_fma_f32 v[4:5], v[134:135], v[4:5], v[24:25]
	v_lshl_add_u64 v[24:25], v[142:143], 1, v[2:3]
	v_cvt_pk_bf16_f32 v2, v18, v19
	v_cvt_pk_bf16_f32 v3, v20, v21
	global_store_dwordx2 v[24:25], v[2:3], off
	v_mul_f32_e32 v2, v19, v19
	v_mul_f32_e32 v3, v21, v21
	v_fmac_f32_e32 v2, v18, v18
	v_fmac_f32_e32 v3, v20, v20
	v_add_f32_e32 v3, v2, v3
	v_cvt_pk_bf16_f32 v2, v10, v11
	v_mul_f32_e32 v11, v11, v11
	v_fmac_f32_e32 v11, v10, v10
	v_mul_f32_e32 v10, v13, v13
	v_fmac_f32_e32 v10, v12, v12
	v_add_f32_e32 v10, v11, v10
	v_add_f32_e32 v3, v3, v10
	v_mul_f32_e32 v10, v7, v7
	v_mul_f32_e32 v11, v9, v9
	v_fmac_f32_e32 v10, v6, v6
	v_fmac_f32_e32 v11, v8, v8
	v_add_f32_e32 v10, v10, v11
	v_add_f32_e32 v3, v3, v10
	v_mul_f32_e32 v10, v23, v23
	v_mul_f32_e32 v11, v5, v5
	v_fmac_f32_e32 v10, v22, v22
	v_fmac_f32_e32 v11, v4, v4
	v_add_f32_e32 v10, v10, v11
	v_add_f32_e32 v10, v3, v10
	v_mov_b32_e32 v11, v10
	s_nop 1
	v_permlane16_swap_b32 v10, v11
	s_nop 1
	v_cvt_pk_bf16_f32 v3, v12, v13
	global_store_dwordx2 v[24:25], v[2:3], off offset:32
	v_cvt_pk_bf16_f32 v6, v6, v7
	v_cvt_pk_bf16_f32 v7, v8, v9
	s_waitcnt lgkmcnt(0)
	v_add_f32_e32 v2, v10, v11
	v_mov_b32_e32 v3, v2
	s_nop 1
	v_permlane32_swap_b32 v2, v3
	s_nop 1
	global_store_dwordx2 v[24:25], v[6:7], off offset:256
	v_cvt_pk_bf16_f32 v6, v22, v23
	v_cvt_pk_bf16_f32 v7, v4, v5
	global_store_dwordx2 v[24:25], v[6:7], off offset:288
	s_and_saveexec_b64 s[24:25], s[0:1]
	s_cbranch_execz .LBB0_656
	v_lshlrev_b64 v[4:5], 6, v[118:119]
	v_lshl_add_u64 v[4:5], s[22:23], 0, v[4:5]
	s_waitcnt lgkmcnt(0)
	v_add_f32_e32 v2, v2, v3
	global_store_dword v[4:5], v2, off
